# NAT bias gather: element constants folded into DS offset immediates (1 address op + 32 ds_read_b32 per tile instead of 96 VALU + 32 reads)
# speedup vs baseline: 1.0095x; 1.0040x over previous
.LBB0_270:
	s_barrier
	ds_write_b128 v126, v[32:35]
	ds_write_b128 v127, v[44:47]
	ds_write_b16 v122, v40 offset:8192
	ds_write_b16_d16_hi v123, v40 offset:8328
	ds_write_b16 v122, v41 offset:8464
	ds_write_b16_d16_hi v123, v41 offset:8600
	ds_write_b16 v122, v42 offset:8736
	ds_write_b16_d16_hi v123, v42 offset:8872
	ds_write_b16 v122, v43 offset:9008
	ds_write_b16_d16_hi v123, v43 offset:9144
	ds_write_b16 v122, v36 offset:9280
	ds_write_b16_d16_hi v123, v36 offset:9416
	ds_write_b16 v122, v37 offset:9552
	ds_write_b16_d16_hi v123, v37 offset:9688
	ds_write_b16 v122, v38 offset:9824
	ds_write_b16_d16_hi v123, v38 offset:9960
	ds_write_b16 v122, v39 offset:10096
	ds_write_b16_d16_hi v123, v39 offset:10232
	s_waitcnt lgkmcnt(0)
	s_barrier
	ds_read_b128 v[32:35], v138
	ds_read_b128 v[36:39], v138 offset:4096
	s_waitcnt lgkmcnt(1)
	v_mfma_f32_32x32x16_bf16 v[48:63], v[32:35], v[64:67], 0
	ds_read_b128 v[146:149], v139
	ds_read_b128 v[150:153], v139 offset:4096
	s_add_i32 s40, s33, s44
	v_cmp_ge_u32_e32 vcc, s40, v115
	v_cmp_lt_u32_e64 s[40:41], s40, v120
	s_and_b64 s[96:97], vcc, s[40:41]
	s_andn2_b64 vcc, exec, s[4:5]
	s_waitcnt lgkmcnt(2)
	v_mfma_f32_32x32x16_bf16 v[32:47], v[36:39], v[64:67], 0
	s_waitcnt lgkmcnt(1)
	v_mfma_f32_32x32x16_bf16 v[48:63], v[146:149], v[68:71], v[48:63]
	s_waitcnt lgkmcnt(0)
	v_mfma_f32_32x32x16_bf16 v[32:47], v[150:153], v[68:71], v[32:47]
	ds_read_b128 v[146:149], v140
	ds_read_b128 v[150:153], v140 offset:4096
	s_waitcnt lgkmcnt(1)
	v_mfma_f32_32x32x16_bf16 v[48:63], v[146:149], v[72:75], v[48:63]
	s_waitcnt lgkmcnt(0)
	v_mfma_f32_32x32x16_bf16 v[32:47], v[150:153], v[72:75], v[32:47]
	ds_read_b128 v[146:149], v141
	ds_read_b128 v[150:153], v141 offset:4096
	s_waitcnt lgkmcnt(1)
	v_mfma_f32_32x32x16_bf16 v[48:63], v[146:149], v[76:79], v[48:63]
	s_waitcnt lgkmcnt(0)
	v_mfma_f32_32x32x16_bf16 v[32:47], v[150:153], v[76:79], v[32:47]
	s_nop 9
	v_mul_f32_e32 v147, 0x3e000000, v48
	v_cndmask_b32_e64 v48, 0, 1, s[4:5]
	v_cmp_ne_u32_e64 s[40:41], 1, v48
	s_cbranch_vccnz .Lnat_np
	v_lshl_add_u32 v222, v124, 2, s78
	ds_read_b32 v190, v222 offset:16660
	ds_read_b32 v191, v222 offset:16668
	ds_read_b32 v192, v222 offset:16692
	ds_read_b32 v193, v222 offset:16700
	ds_read_b32 v194, v222 offset:16724
	ds_read_b32 v195, v222 offset:16732
	ds_read_b32 v196, v222 offset:16756
	ds_read_b32 v197, v222 offset:16764
	ds_read_b32 v198, v222 offset:16788
	ds_read_b32 v199, v222 offset:16796
	ds_read_b32 v200, v222 offset:16820
	ds_read_b32 v201, v222 offset:16828
	ds_read_b32 v202, v222 offset:16852
	ds_read_b32 v203, v222 offset:16860
	ds_read_b32 v204, v222 offset:16884
	ds_read_b32 v205, v222 offset:16892
	ds_read_b32 v206, v222 offset:16664
	ds_read_b32 v207, v222 offset:16672
	ds_read_b32 v208, v222 offset:16696
	ds_read_b32 v209, v222 offset:16704
	ds_read_b32 v210, v222 offset:16728
	ds_read_b32 v211, v222 offset:16736
	ds_read_b32 v212, v222 offset:16760
	ds_read_b32 v213, v222 offset:16768
	ds_read_b32 v214, v222 offset:16792
	ds_read_b32 v215, v222 offset:16800
	ds_read_b32 v216, v222 offset:16824
	ds_read_b32 v217, v222 offset:16832
	ds_read_b32 v218, v222 offset:16856
	ds_read_b32 v219, v222 offset:16864
	ds_read_b32 v220, v222 offset:16888
	ds_read_b32 v221, v222 offset:16896
	s_waitcnt lgkmcnt(0)
	s_and_b64 vcc, s[96:97], s[64:65]
	v_add_f32_e32 v48, v147, v190
	v_cndmask_b32_e32 v147, v169, v48, vcc
	v_mul_f32_e32 v146, 0x3e000000, v49
	s_and_b64 vcc, s[96:97], s[66:67]
	v_add_f32_e32 v48, v146, v206
	v_cndmask_b32_e32 v146, v169, v48, vcc
	v_mul_f32_e32 v119, 0x3e000000, v50
	s_and_b64 vcc, s[96:97], s[68:69]
	v_add_f32_e32 v48, v119, v191
	v_cndmask_b32_e32 v119, v169, v48, vcc
	v_mul_f32_e32 v145, 0x3e000000, v51
	s_and_b64 vcc, s[96:97], s[70:71]
	v_add_f32_e32 v48, v145, v207
	v_cndmask_b32_e32 v145, v169, v48, vcc
	v_mul_f32_e32 v51, 0x3e000000, v52
	s_and_b64 vcc, s[96:97], s[72:73]
	v_add_f32_e32 v48, v51, v192
	v_cndmask_b32_e32 v51, v169, v48, vcc
	v_mul_f32_e32 v52, 0x3e000000, v53
	s_and_b64 vcc, s[96:97], s[74:75]
	v_add_f32_e32 v48, v52, v208
	v_cndmask_b32_e32 v52, v169, v48, vcc
	v_mul_f32_e32 v48, 0x3e000000, v54
	v_readlane_b32 s4, v254, 45
	v_readlane_b32 s5, v254, 46
	s_and_b64 vcc, s[96:97], s[4:5]
	v_add_f32_e32 v48, v48, v193
	v_cndmask_b32_e32 v48, v169, v48, vcc
	v_mul_f32_e32 v50, 0x3e000000, v55
	v_readlane_b32 s4, v254, 47
	v_readlane_b32 s5, v254, 48
	s_and_b64 vcc, s[96:97], s[4:5]
	v_add_f32_e32 v49, v50, v209
	v_cndmask_b32_e32 v50, v169, v49, vcc
	v_mul_f32_e32 v49, 0x3e000000, v56
	v_readlane_b32 s4, v254, 49
	v_readlane_b32 s5, v254, 50
	v_readlane_b32 vcc_lo, v254, 51
	s_and_b64 s[4:5], s[96:97], s[4:5]
	v_readlane_b32 vcc_hi, v254, 52
	s_and_b64 vcc, s[4:5], vcc
	v_add_f32_e32 v49, v49, v194
	v_cndmask_b32_e32 v49, v169, v49, vcc
	v_mul_f32_e32 v53, 0x3e000000, v57
	v_readlane_b32 s4, v254, 53
	v_readlane_b32 s5, v254, 54
	v_readlane_b32 vcc_lo, v254, 55
	s_and_b64 s[4:5], s[96:97], s[4:5]
	v_readlane_b32 vcc_hi, v254, 56
	s_and_b64 vcc, s[4:5], vcc
	v_add_f32_e32 v53, v53, v210
	v_cndmask_b32_e32 v53, v169, v53, vcc
	v_mul_f32_e32 v54, 0x3e000000, v58
	v_readlane_b32 s4, v254, 57
	v_readlane_b32 s5, v254, 58
	v_readlane_b32 vcc_lo, v255, 26
	s_and_b64 s[4:5], s[96:97], s[4:5]
	v_readlane_b32 vcc_hi, v255, 27
	s_and_b64 vcc, s[4:5], vcc
	v_add_f32_e32 v54, v54, v195
	v_cndmask_b32_e32 v54, v169, v54, vcc
	v_mul_f32_e32 v55, 0x3e000000, v59
	v_readlane_b32 s4, v255, 28
	v_readlane_b32 s5, v255, 29
	v_readlane_b32 vcc_lo, v255, 30
	s_and_b64 s[4:5], s[96:97], s[4:5]
	v_readlane_b32 vcc_hi, v255, 31
	s_and_b64 vcc, s[4:5], vcc
	v_add_f32_e32 v55, v55, v211
	v_cndmask_b32_e32 v55, v169, v55, vcc
	v_mul_f32_e32 v56, 0x3e000000, v60
	v_readlane_b32 s4, v255, 32
	v_readlane_b32 s5, v255, 33
	v_readlane_b32 vcc_lo, v255, 34
	s_and_b64 s[4:5], s[96:97], s[4:5]
	v_readlane_b32 vcc_hi, v255, 35
	s_and_b64 vcc, s[4:5], vcc
	v_add_f32_e32 v56, v56, v196
	v_cndmask_b32_e32 v56, v169, v56, vcc
	v_mul_f32_e32 v57, 0x3e000000, v61
	v_readlane_b32 s4, v255, 36
	v_readlane_b32 s5, v255, 37
	v_readlane_b32 vcc_lo, v255, 38
	s_and_b64 s[4:5], s[96:97], s[4:5]
	v_readlane_b32 vcc_hi, v255, 39
	s_and_b64 vcc, s[4:5], vcc
	v_add_f32_e32 v57, v57, v212
	v_cndmask_b32_e32 v57, v169, v57, vcc
	v_mul_f32_e32 v58, 0x3e000000, v62
	v_readlane_b32 s4, v255, 40
	v_readlane_b32 s5, v255, 41
	v_readlane_b32 vcc_lo, v255, 42
	s_and_b64 s[4:5], s[96:97], s[4:5]
	v_readlane_b32 vcc_hi, v255, 43
	s_and_b64 vcc, s[4:5], vcc
	v_add_f32_e32 v58, v58, v197
	v_cndmask_b32_e32 v58, v169, v58, vcc
	v_mul_f32_e32 v59, 0x3e000000, v63
	v_readlane_b32 s4, v255, 44
	v_readlane_b32 s5, v255, 45
	v_readlane_b32 vcc_lo, v255, 46
	s_and_b64 s[4:5], s[96:97], s[4:5]
	v_readlane_b32 vcc_hi, v255, 47
	s_and_b64 vcc, s[4:5], vcc
	v_add_f32_e32 v59, v59, v213
	v_cndmask_b32_e32 v59, v169, v59, vcc
	v_mul_f32_e32 v60, 0x3e000000, v32
	v_readlane_b32 s4, v255, 48
	v_readlane_b32 s5, v255, 49
	v_readlane_b32 vcc_lo, v255, 50
	s_and_b64 s[4:5], s[96:97], s[4:5]
	v_readlane_b32 vcc_hi, v255, 51
	s_and_b64 vcc, s[4:5], vcc
	v_add_f32_e32 v32, v60, v198
	v_cndmask_b32_e32 v60, v169, v32, vcc
	v_mul_f32_e32 v61, 0x3e000000, v33
	v_readlane_b32 s4, v255, 52
	v_readlane_b32 s5, v255, 53
	v_readlane_b32 vcc_lo, v255, 54
	s_and_b64 s[4:5], s[96:97], s[4:5]
	v_readlane_b32 vcc_hi, v255, 55
	s_and_b64 vcc, s[4:5], vcc
	v_add_f32_e32 v32, v61, v214
	v_cndmask_b32_e32 v61, v169, v32, vcc
	v_mul_f32_e32 v62, 0x3e000000, v34
	v_readlane_b32 s4, v255, 56
	v_readlane_b32 s5, v255, 57
	v_readlane_b32 vcc_lo, v255, 58
	s_and_b64 s[4:5], s[96:97], s[4:5]
	v_readlane_b32 vcc_hi, v255, 59
	s_and_b64 vcc, s[4:5], vcc
	v_add_f32_e32 v32, v62, v199
	v_cndmask_b32_e32 v62, v169, v32, vcc
	v_mul_f32_e32 v150, 0x3e000000, v35
	v_readlane_b32 s4, v255, 60
	v_readlane_b32 s5, v255, 61
	v_readlane_b32 vcc_lo, v255, 62
	s_and_b64 s[4:5], s[96:97], s[4:5]
	v_readlane_b32 vcc_hi, v255, 63
	s_and_b64 vcc, s[4:5], vcc
	v_add_f32_e32 v32, v150, v215
	v_cndmask_b32_e32 v150, v169, v32, vcc
	v_mul_f32_e32 v151, 0x3e000000, v36
	s_and_b64 s[4:5], s[96:97], s[6:7]
	s_and_b64 vcc, s[4:5], s[8:9]
	v_add_f32_e32 v32, v151, v200
	v_cndmask_b32_e32 v151, v169, v32, vcc
	v_mul_f32_e32 v153, 0x3e000000, v37
	s_and_b64 s[4:5], s[96:97], s[10:11]
	s_and_b64 vcc, s[4:5], s[12:13]
	v_add_f32_e32 v32, v153, v216
	v_cndmask_b32_e32 v153, v169, v32, vcc
	v_mul_f32_e32 v149, 0x3e000000, v38
	s_and_b64 s[4:5], s[96:97], s[14:15]
	s_and_b64 vcc, s[4:5], s[16:17]
	v_add_f32_e32 v32, v149, v201
	v_cndmask_b32_e32 v149, v169, v32, vcc
	v_mul_f32_e32 v152, 0x3e000000, v39
	s_and_b64 s[4:5], s[96:97], s[18:19]
	s_and_b64 vcc, s[4:5], s[20:21]
	v_add_f32_e32 v32, v152, v217
	v_cndmask_b32_e32 v152, v169, v32, vcc
	v_mul_f32_e32 v63, 0x3e000000, v40
	s_and_b64 vcc, s[96:97], s[22:23]
	v_add_f32_e32 v32, v63, v202
	v_cndmask_b32_e32 v63, v169, v32, vcc
	v_mul_f32_e32 v148, 0x3e000000, v41
	s_and_b64 vcc, s[96:97], s[24:25]
	v_add_f32_e32 v32, v148, v218
	v_cndmask_b32_e32 v148, v169, v32, vcc
	v_mul_f32_e32 v41, 0x3e000000, v42
	s_and_b64 vcc, s[96:97], s[26:27]
	v_add_f32_e32 v32, v41, v203
	v_cndmask_b32_e32 v41, v169, v32, vcc
	v_mul_f32_e32 v42, 0x3e000000, v43
	s_and_b64 vcc, s[96:97], s[28:29]
	v_add_f32_e32 v32, v42, v219
	v_cndmask_b32_e32 v42, v169, v32, vcc
	v_mul_f32_e32 v39, 0x3e000000, v44
	s_and_b64 vcc, s[96:97], s[30:31]
	v_add_f32_e32 v32, v39, v204
	v_cndmask_b32_e32 v39, v169, v32, vcc
	v_mul_f32_e32 v45, 0x3e000000, v45
	s_and_b64 vcc, s[96:97], s[34:35]
	v_add_f32_e32 v32, v45, v220
	v_cndmask_b32_e32 v45, v169, v32, vcc
	v_mul_f32_e32 v46, 0x3e000000, v46
	s_and_b64 vcc, s[96:97], s[0:1]
	v_add_f32_e32 v32, v46, v205
	v_cndmask_b32_e32 v46, v169, v32, vcc
	v_mul_f32_e32 v154, 0x3e000000, v47
	s_and_b64 vcc, s[96:97], s[38:39]
	v_add_f32_e32 v32, v154, v221
	v_cndmask_b32_e32 v154, v169, v32, vcc
	s_branch .LBB0_334
